# gate/up K-loop back edge rotated: counter/pointer updates and next-tile selects moved from after the loop-back barrier to before it
# baseline (speedup 1.0000x reference)
.LBB0_1097:
	s_add_u32 s28, s26, 0xfffc0080
	s_addc_u32 s29, s27, -1
	s_add_i32 s59, 0, 0x10000
	s_cmp_eq_u32 s58, 12
	s_cselect_b32 s31, s19, s29
	s_cselect_b32 s30, s25, s28
	s_cselect_b32 s29, s17, s57
	s_cselect_b32 s28, s53, s56
	s_add_i32 s60, 0, 0x14000
.Lgu_body:
	v_add_u32_e32 v140, s59, v143
	ds_read_b128 v[150:153], v140
	ds_read_b128 v[154:157], v140 offset:1024
	ds_read_b128 v[158:161], v140 offset:2048
	ds_read_b128 v[162:165], v140 offset:3072
	v_add_u32_e32 v140, s60, v143
	ds_read_b128 v[166:169], v140
	ds_read_b128 v[180:183], v140 offset:1024
	ds_read_b128 v[184:187], v140 offset:2048
	ds_read_b128 v[188:191], v140 offset:3072
	v_lshl_add_u64 v[140:141], s[26:27], 0, v[136:137]
	s_add_i32 m0, s41, 0xc000
	ds_read_b128 v[192:195], v149
	ds_read_b128 v[196:199], v149 offset:1024
	ds_read_b128 v[200:203], v149 offset:2048
	ds_read_b128 v[204:207], v149 offset:3072
	ds_read_b128 v[208:211], v149 offset:4096
	ds_read_b128 v[212:215], v149 offset:5120
	ds_read_b128 v[216:219], v149 offset:6144
	ds_read_b128 v[236:239], v149 offset:7168
	global_load_lds_dwordx4 v[140:141], off
	v_lshl_add_u64 v[140:141], s[26:27], 0, v[138:139]
	s_add_i32 m0, s41, 0xe000
	s_nop 0
	global_load_lds_dwordx4 v[140:141], off
	s_waitcnt vmcnt(8)
	s_waitcnt lgkmcnt(0)
	s_barrier
	s_setprio 1
	v_mfma_f32_16x16x32_bf16 v[126:129], v[150:153], v[192:195], v[126:129]
	v_mfma_f32_16x16x32_bf16 v[118:121], v[158:161], v[192:195], v[118:121]
	v_mfma_f32_16x16x32_bf16 v[110:113], v[150:153], v[200:203], v[110:113]
	v_mfma_f32_16x16x32_bf16 v[102:105], v[158:161], v[200:203], v[102:105]
	v_mfma_f32_16x16x32_bf16 v[94:97], v[150:153], v[208:211], v[94:97]
	v_mfma_f32_16x16x32_bf16 v[86:89], v[158:161], v[208:211], v[86:89]
	v_mfma_f32_16x16x32_bf16 v[78:81], v[150:153], v[216:219], v[78:81]
	v_mfma_f32_16x16x32_bf16 v[70:73], v[158:161], v[216:219], v[70:73]
	v_mfma_f32_16x16x32_bf16 v[126:129], v[154:157], v[196:199], v[126:129]
	v_mfma_f32_16x16x32_bf16 v[118:121], v[162:165], v[196:199], v[118:121]
	v_mfma_f32_16x16x32_bf16 v[110:113], v[154:157], v[204:207], v[110:113]
	v_mfma_f32_16x16x32_bf16 v[102:105], v[162:165], v[204:207], v[102:105]
	v_mfma_f32_16x16x32_bf16 v[94:97], v[154:157], v[212:215], v[94:97]
	v_mfma_f32_16x16x32_bf16 v[86:89], v[162:165], v[212:215], v[86:89]
	v_mfma_f32_16x16x32_bf16 v[78:81], v[154:157], v[236:239], v[78:81]
	v_mfma_f32_16x16x32_bf16 v[70:73], v[162:165], v[236:239], v[70:73]
	s_setprio 0
	s_setprio 1
	v_mfma_f32_16x16x32_bf16 v[122:125], v[166:169], v[192:195], v[122:125]
	v_mfma_f32_16x16x32_bf16 v[114:117], v[184:187], v[192:195], v[114:117]
	v_mfma_f32_16x16x32_bf16 v[106:109], v[166:169], v[200:203], v[106:109]
	v_mfma_f32_16x16x32_bf16 v[98:101], v[184:187], v[200:203], v[98:101]
	v_mfma_f32_16x16x32_bf16 v[90:93], v[166:169], v[208:211], v[90:93]
	v_mfma_f32_16x16x32_bf16 v[82:85], v[184:187], v[208:211], v[82:85]
	v_mfma_f32_16x16x32_bf16 v[74:77], v[166:169], v[216:219], v[74:77]
	v_mfma_f32_16x16x32_bf16 v[66:69], v[184:187], v[216:219], v[66:69]
	v_mfma_f32_16x16x32_bf16 v[122:125], v[180:183], v[196:199], v[122:125]
	v_mfma_f32_16x16x32_bf16 v[114:117], v[188:191], v[196:199], v[114:117]
	v_mfma_f32_16x16x32_bf16 v[106:109], v[180:183], v[204:207], v[106:109]
	v_mfma_f32_16x16x32_bf16 v[98:101], v[188:191], v[204:207], v[98:101]
	v_mfma_f32_16x16x32_bf16 v[90:93], v[180:183], v[212:215], v[90:93]
	v_mfma_f32_16x16x32_bf16 v[82:85], v[188:191], v[212:215], v[82:85]
	v_mfma_f32_16x16x32_bf16 v[74:77], v[180:183], v[236:239], v[74:77]
	v_mfma_f32_16x16x32_bf16 v[66:69], v[188:191], v[236:239], v[66:69]
	s_setprio 0
	s_barrier
	s_add_i32 s59, s59, s38
	v_lshl_add_u64 v[140:141], s[28:29], 0, v[0:1]
	s_mov_b32 m0, s59
	ds_read_b128 v[192:195], v149 offset:16384
	ds_read_b128 v[196:199], v149 offset:17408
	ds_read_b128 v[200:203], v149 offset:18432
	ds_read_b128 v[204:207], v149 offset:19456
	ds_read_b128 v[208:211], v149 offset:20480
	ds_read_b128 v[212:215], v149 offset:21504
	ds_read_b128 v[216:219], v149 offset:22528
	ds_read_b128 v[236:239], v149 offset:23552
	global_load_lds_dwordx4 v[140:141], off
	s_add_i32 m0, s59, 0x2000
	s_add_u32 s64, s28, 0x40000
	v_lshl_add_u64 v[222:223], s[28:29], 0, v[130:131]
	s_addc_u32 s65, s29, 0
	s_add_i32 s59, s60, s38
	global_load_lds_dwordx4 v[222:223], off
	v_lshl_add_u64 v[232:233], s[64:65], 0, v[0:1]
	s_mov_b32 m0, s59
	v_lshl_add_u64 v[240:241], s[30:31], 0, v[132:133]
	global_load_lds_dwordx4 v[232:233], off
	v_lshl_add_u64 v[232:233], s[64:65], 0, v[130:131]
	s_add_i32 m0, s59, 0x2000
	s_nop 0
	global_load_lds_dwordx4 v[232:233], off
	v_lshl_add_u64 v[232:233], s[30:31], 0, v[134:135]
	s_mov_b32 m0, s41
	s_nop 0
	global_load_lds_dwordx4 v[232:233], off
	s_mov_b32 m0, s42
	s_nop 0
	global_load_lds_dwordx4 v[240:241], off
	s_waitcnt vmcnt(8)
	s_waitcnt lgkmcnt(0)
	s_barrier
	s_setprio 1
	v_mfma_f32_16x16x32_bf16 v[62:65], v[150:153], v[192:195], v[62:65]
	v_mfma_f32_16x16x32_bf16 v[54:57], v[158:161], v[192:195], v[54:57]
	v_mfma_f32_16x16x32_bf16 v[46:49], v[150:153], v[200:203], v[46:49]
	v_mfma_f32_16x16x32_bf16 v[38:41], v[158:161], v[200:203], v[38:41]
	v_mfma_f32_16x16x32_bf16 v[30:33], v[150:153], v[208:211], v[30:33]
	v_mfma_f32_16x16x32_bf16 v[22:25], v[158:161], v[208:211], v[22:25]
	v_mfma_f32_16x16x32_bf16 v[14:17], v[150:153], v[216:219], v[14:17]
	v_mfma_f32_16x16x32_bf16 v[6:9], v[158:161], v[216:219], v[6:9]
	v_mfma_f32_16x16x32_bf16 v[62:65], v[154:157], v[196:199], v[62:65]
	v_mfma_f32_16x16x32_bf16 v[54:57], v[162:165], v[196:199], v[54:57]
	v_mfma_f32_16x16x32_bf16 v[46:49], v[154:157], v[204:207], v[46:49]
	v_mfma_f32_16x16x32_bf16 v[38:41], v[162:165], v[204:207], v[38:41]
	v_mfma_f32_16x16x32_bf16 v[30:33], v[154:157], v[212:215], v[30:33]
	v_mfma_f32_16x16x32_bf16 v[22:25], v[162:165], v[212:215], v[22:25]
	v_mfma_f32_16x16x32_bf16 v[14:17], v[154:157], v[236:239], v[14:17]
	v_mfma_f32_16x16x32_bf16 v[6:9], v[162:165], v[236:239], v[6:9]
	s_setprio 0
	s_setprio 1
	v_mfma_f32_16x16x32_bf16 v[58:61], v[166:169], v[192:195], v[58:61]
	v_mfma_f32_16x16x32_bf16 v[50:53], v[184:187], v[192:195], v[50:53]
	v_mfma_f32_16x16x32_bf16 v[42:45], v[166:169], v[200:203], v[42:45]
	v_mfma_f32_16x16x32_bf16 v[34:37], v[184:187], v[200:203], v[34:37]
	v_mfma_f32_16x16x32_bf16 v[26:29], v[166:169], v[208:211], v[26:29]
	v_mfma_f32_16x16x32_bf16 v[18:21], v[184:187], v[208:211], v[18:21]
	v_mfma_f32_16x16x32_bf16 v[10:13], v[166:169], v[216:219], v[10:13]
	v_mfma_f32_16x16x32_bf16 v[2:5], v[184:187], v[216:219], v[2:5]
	v_mfma_f32_16x16x32_bf16 v[58:61], v[180:183], v[196:199], v[58:61]
	v_mfma_f32_16x16x32_bf16 v[50:53], v[188:191], v[196:199], v[50:53]
	v_mfma_f32_16x16x32_bf16 v[42:45], v[180:183], v[204:207], v[42:45]
	v_mfma_f32_16x16x32_bf16 v[34:37], v[188:191], v[204:207], v[34:37]
	v_mfma_f32_16x16x32_bf16 v[26:29], v[180:183], v[212:215], v[26:29]
	v_mfma_f32_16x16x32_bf16 v[18:21], v[188:191], v[212:215], v[18:21]
	v_mfma_f32_16x16x32_bf16 v[10:13], v[180:183], v[236:239], v[10:13]
	v_mfma_f32_16x16x32_bf16 v[2:5], v[188:191], v[236:239], v[2:5]
	s_setprio 0
	s_barrier
	s_add_i32 s59, 0, 0x18000
	s_add_i32 s60, 0, 0x1c000
	v_add_u32_e32 v162, s59, v143
	v_add_u32_e32 v188, s60, v143
	ds_read_b128 v[150:153], v162
	ds_read_b128 v[154:157], v162 offset:1024
	ds_read_b128 v[158:161], v162 offset:2048
	ds_read_b128 v[162:165], v162 offset:3072
	ds_read_b128 v[166:169], v188
	ds_read_b128 v[180:183], v188 offset:1024
	ds_read_b128 v[184:187], v188 offset:2048
	ds_read_b128 v[188:191], v188 offset:3072
	s_add_u32 s30, s30, 0x40000
	s_addc_u32 s31, s31, 0
	s_mov_b32 m0, s43
	v_lshl_add_u64 v[242:243], s[30:31], 0, v[134:135]
	ds_read_b128 v[192:195], v149 offset:32768
	ds_read_b128 v[196:199], v149 offset:33792
	ds_read_b128 v[200:203], v149 offset:34816
	ds_read_b128 v[204:207], v149 offset:35840
	ds_read_b128 v[208:211], v149 offset:36864
	ds_read_b128 v[212:215], v149 offset:37888
	ds_read_b128 v[216:219], v149 offset:38912
	ds_read_b128 v[236:239], v149 offset:39936
	global_load_lds_dwordx4 v[242:243], off
	v_lshl_add_u64 v[242:243], s[30:31], 0, v[132:133]
	s_mov_b32 m0, s46
	s_nop 0
	global_load_lds_dwordx4 v[242:243], off
	s_waitcnt vmcnt(8)
	s_waitcnt lgkmcnt(0)
	s_barrier
	s_setprio 1
	v_mfma_f32_16x16x32_bf16 v[126:129], v[150:153], v[192:195], v[126:129]
	v_mfma_f32_16x16x32_bf16 v[118:121], v[158:161], v[192:195], v[118:121]
	v_mfma_f32_16x16x32_bf16 v[110:113], v[150:153], v[200:203], v[110:113]
	v_mfma_f32_16x16x32_bf16 v[102:105], v[158:161], v[200:203], v[102:105]
	v_mfma_f32_16x16x32_bf16 v[94:97], v[150:153], v[208:211], v[94:97]
	v_mfma_f32_16x16x32_bf16 v[86:89], v[158:161], v[208:211], v[86:89]
	v_mfma_f32_16x16x32_bf16 v[78:81], v[150:153], v[216:219], v[78:81]
	v_mfma_f32_16x16x32_bf16 v[70:73], v[158:161], v[216:219], v[70:73]
	v_mfma_f32_16x16x32_bf16 v[126:129], v[154:157], v[196:199], v[126:129]
	v_mfma_f32_16x16x32_bf16 v[118:121], v[162:165], v[196:199], v[118:121]
	v_mfma_f32_16x16x32_bf16 v[110:113], v[154:157], v[204:207], v[110:113]
	v_mfma_f32_16x16x32_bf16 v[102:105], v[162:165], v[204:207], v[102:105]
	v_mfma_f32_16x16x32_bf16 v[94:97], v[154:157], v[212:215], v[94:97]
	v_mfma_f32_16x16x32_bf16 v[86:89], v[162:165], v[212:215], v[86:89]
	v_mfma_f32_16x16x32_bf16 v[78:81], v[154:157], v[236:239], v[78:81]
	v_mfma_f32_16x16x32_bf16 v[70:73], v[162:165], v[236:239], v[70:73]
	s_setprio 0
	s_setprio 1
	v_mfma_f32_16x16x32_bf16 v[122:125], v[166:169], v[192:195], v[122:125]
	v_mfma_f32_16x16x32_bf16 v[114:117], v[184:187], v[192:195], v[114:117]
	v_mfma_f32_16x16x32_bf16 v[106:109], v[166:169], v[200:203], v[106:109]
	v_mfma_f32_16x16x32_bf16 v[98:101], v[184:187], v[200:203], v[98:101]
	v_mfma_f32_16x16x32_bf16 v[90:93], v[166:169], v[208:211], v[90:93]
	v_mfma_f32_16x16x32_bf16 v[82:85], v[184:187], v[208:211], v[82:85]
	v_mfma_f32_16x16x32_bf16 v[74:77], v[166:169], v[216:219], v[74:77]
	v_mfma_f32_16x16x32_bf16 v[66:69], v[184:187], v[216:219], v[66:69]
	v_mfma_f32_16x16x32_bf16 v[122:125], v[180:183], v[196:199], v[122:125]
	v_mfma_f32_16x16x32_bf16 v[114:117], v[188:191], v[196:199], v[114:117]
	v_mfma_f32_16x16x32_bf16 v[106:109], v[180:183], v[204:207], v[106:109]
	v_mfma_f32_16x16x32_bf16 v[98:101], v[188:191], v[204:207], v[98:101]
	v_mfma_f32_16x16x32_bf16 v[90:93], v[180:183], v[212:215], v[90:93]
	v_mfma_f32_16x16x32_bf16 v[82:85], v[188:191], v[212:215], v[82:85]
	v_mfma_f32_16x16x32_bf16 v[74:77], v[180:183], v[236:239], v[74:77]
	v_mfma_f32_16x16x32_bf16 v[66:69], v[188:191], v[236:239], v[66:69]
	s_setprio 0
	s_barrier
	s_add_i32 s30, s59, s38
	v_lshl_add_u64 v[140:141], v[140:141], 0, s[54:55]
	s_mov_b32 m0, s30
	ds_read_b128 v[192:195], v149 offset:49152
	ds_read_b128 v[196:199], v149 offset:50176
	ds_read_b128 v[200:203], v149 offset:51200
	ds_read_b128 v[204:207], v149 offset:52224
	ds_read_b128 v[208:211], v149 offset:53248
	ds_read_b128 v[212:215], v149 offset:54272
	ds_read_b128 v[216:219], v149 offset:55296
	ds_read_b128 v[236:239], v149 offset:56320
	global_load_lds_dwordx4 v[140:141], off
	s_add_i32 m0, s30, 0x2000
	s_add_u32 s28, s28, 0x40080
	v_lshl_add_u64 v[140:141], v[222:223], 0, s[54:55]
	s_addc_u32 s29, s29, 0
	s_add_i32 s30, s60, s38
	global_load_lds_dwordx4 v[140:141], off
	v_lshl_add_u64 v[140:141], s[28:29], 0, v[0:1]
	s_mov_b32 m0, s30
	s_nop 0
	global_load_lds_dwordx4 v[140:141], off
	v_lshl_add_u64 v[140:141], s[28:29], 0, v[130:131]
	s_add_i32 m0, s30, 0x2000
	s_nop 0
	global_load_lds_dwordx4 v[140:141], off
	v_lshl_add_u64 v[140:141], v[232:233], 0, s[54:55]
	s_mov_b32 m0, s47
	s_nop 0
	global_load_lds_dwordx4 v[140:141], off
	v_lshl_add_u64 v[140:141], v[240:241], 0, s[54:55]
	s_mov_b32 m0, s50
	s_nop 0
	global_load_lds_dwordx4 v[140:141], off
	s_waitcnt vmcnt(8)
	s_waitcnt lgkmcnt(0)
	s_barrier
	s_setprio 1
	v_mfma_f32_16x16x32_bf16 v[62:65], v[150:153], v[192:195], v[62:65]
	v_mfma_f32_16x16x32_bf16 v[54:57], v[158:161], v[192:195], v[54:57]
	v_mfma_f32_16x16x32_bf16 v[46:49], v[150:153], v[200:203], v[46:49]
	v_mfma_f32_16x16x32_bf16 v[38:41], v[158:161], v[200:203], v[38:41]
	v_mfma_f32_16x16x32_bf16 v[30:33], v[150:153], v[208:211], v[30:33]
	v_mfma_f32_16x16x32_bf16 v[22:25], v[158:161], v[208:211], v[22:25]
	v_mfma_f32_16x16x32_bf16 v[14:17], v[150:153], v[216:219], v[14:17]
	v_mfma_f32_16x16x32_bf16 v[6:9], v[158:161], v[216:219], v[6:9]
	v_mfma_f32_16x16x32_bf16 v[62:65], v[154:157], v[196:199], v[62:65]
	v_mfma_f32_16x16x32_bf16 v[54:57], v[162:165], v[196:199], v[54:57]
	v_mfma_f32_16x16x32_bf16 v[46:49], v[154:157], v[204:207], v[46:49]
	v_mfma_f32_16x16x32_bf16 v[38:41], v[162:165], v[204:207], v[38:41]
	v_mfma_f32_16x16x32_bf16 v[30:33], v[154:157], v[212:215], v[30:33]
	v_mfma_f32_16x16x32_bf16 v[22:25], v[162:165], v[212:215], v[22:25]
	v_mfma_f32_16x16x32_bf16 v[14:17], v[154:157], v[236:239], v[14:17]
	v_mfma_f32_16x16x32_bf16 v[6:9], v[162:165], v[236:239], v[6:9]
	s_setprio 0
	s_setprio 1
	v_mfma_f32_16x16x32_bf16 v[58:61], v[166:169], v[192:195], v[58:61]
	v_mfma_f32_16x16x32_bf16 v[50:53], v[184:187], v[192:195], v[50:53]
	v_mfma_f32_16x16x32_bf16 v[42:45], v[166:169], v[200:203], v[42:45]
	v_mfma_f32_16x16x32_bf16 v[34:37], v[184:187], v[200:203], v[34:37]
	v_mfma_f32_16x16x32_bf16 v[26:29], v[166:169], v[208:211], v[26:29]
	v_mfma_f32_16x16x32_bf16 v[18:21], v[184:187], v[208:211], v[18:21]
	v_mfma_f32_16x16x32_bf16 v[10:13], v[166:169], v[216:219], v[10:13]
	v_mfma_f32_16x16x32_bf16 v[2:5], v[184:187], v[216:219], v[2:5]
	v_mfma_f32_16x16x32_bf16 v[58:61], v[180:183], v[196:199], v[58:61]
	v_mfma_f32_16x16x32_bf16 v[50:53], v[188:191], v[196:199], v[50:53]
	v_mfma_f32_16x16x32_bf16 v[42:45], v[180:183], v[204:207], v[42:45]
	v_mfma_f32_16x16x32_bf16 v[34:37], v[188:191], v[204:207], v[34:37]
	v_mfma_f32_16x16x32_bf16 v[26:29], v[180:183], v[212:215], v[26:29]
	v_mfma_f32_16x16x32_bf16 v[18:21], v[188:191], v[212:215], v[18:21]
	v_mfma_f32_16x16x32_bf16 v[10:13], v[180:183], v[236:239], v[10:13]
	v_mfma_f32_16x16x32_bf16 v[2:5], v[188:191], v[236:239], v[2:5]
	s_add_i32 s58, s58, 2
	s_add_u32 s26, s26, 0x100
	s_addc_u32 s27, s27, 0
	s_add_u32 s56, s56, 0x100
	s_addc_u32 s57, s57, 0
	s_cmp_gt_u32 s58, 13
	s_cbranch_scc1 .Lgu_exit
	s_add_u32 s28, s26, 0xfffc0080
	s_addc_u32 s29, s27, -1
	s_add_i32 s59, 0, 0x10000
	s_cmp_eq_u32 s58, 12
	s_cselect_b32 s31, s19, s29
	s_cselect_b32 s30, s25, s28
	s_cselect_b32 s29, s17, s57
	s_cselect_b32 s28, s53, s56
	s_add_i32 s60, 0, 0x14000
	s_setprio 0
	s_barrier
	s_branch .Lgu_body
.Lgu_exit:
	s_setprio 0
	s_barrier
	s_and_b64 vcc, exec, s[14:15]
	s_cbranch_vccz .LBB0_1100
	s_barrier
